# post phase: workgroups 256..511 start ~7us late (phase offset of the two workgroups of a CU), on top of mixer 10us stagger
# baseline (speedup 1.0000x reference)
.LBB0_582:
	s_or_b64 exec, exec, s[4:5]
	v_readlane_b32 s4, v254, 3
	v_readlane_b32 s5, v254, 4
	s_andn2_b64 vcc, exec, s[4:5]
	s_barrier
	s_cbranch_vccnz .LBB0_637
	v_readlane_b32 s10, v254, 57
	s_mul_i32 s4, s10, 0xb00000
	s_add_u32 s16, s74, s4
	s_addc_u32 s17, s75, 0
	s_add_u32 s18, s72, s4
	s_addc_u32 s19, s73, 0
	s_add_u32 s20, s70, s4
	v_readlane_b32 s4, v254, 59
	v_readlane_b32 s5, v254, 60
	s_mov_b32 s5, s91
	v_readlane_b32 s48, v253, 26
	s_addc_u32 s21, s71, 0
	s_lshl_b64 s[4:5], s[4:5], 2
	v_readlane_b32 s58, v253, 36
	v_readlane_b32 s59, v253, 37
	s_add_u32 s6, s58, s4
	v_readlane_b32 s60, v253, 38
	s_addc_u32 s7, s59, s5
	v_readlane_b32 s11, v254, 58
	v_readlane_b32 s61, v253, 39
	s_add_u32 s8, s60, s4
	s_addc_u32 s9, s61, s5
	s_lshl_b32 s24, s10, 8
	s_lshl_b64 s[4:5], s[10:11], 17
	v_readlane_b32 s10, v254, 21
	s_add_u32 s10, s10, s4
	v_readlane_b32 s4, v254, 22
	s_addc_u32 s11, s4, s5
	v_readlane_b32 s25, v254, 13
	v_readlane_b32 s49, v253, 27
	v_readlane_b32 s50, v253, 28
	v_readlane_b32 s51, v253, 29
	v_readlane_b32 s52, v253, 30
	v_readlane_b32 s53, v253, 31
	v_readlane_b32 s54, v253, 32
	v_readlane_b32 s55, v253, 33
	v_readlane_b32 s56, v253, 34
	v_readlane_b32 s57, v253, 35
	v_readlane_b32 s62, v253, 40
	v_readlane_b32 s63, v253, 41
	v_readlane_b32 s4, v254, 13
	s_cmpk_lt_u32 s4, 0x100
	s_cbranch_scc1 .Ldq_nodelay
	s_sleep 127
	s_sleep 127
.Ldq_nodelay:
	s_branch .LBB0_585
.LBB0_584:
	s_add_i32 s25, s25, s38
	s_cmpk_gt_i32 s25, 0x143f
	s_cbranch_scc1 .LBB0_637
